# MLA unit lists rebalanced v2 from measured unit times: 2-tile WGs +1 uq; 64 WGs tile+cache ukv+uq+2 ukv; 48 WGs tile+3 uq; 64 WGs tile+4 ukv
# speedup vs baseline: 1.0103x; 1.0103x over previous
.LBB0_88:
	s_andn2_b64 vcc, exec, s[2:3]
	s_mov_b64 s[6:7], 0
	s_cbranch_vccnz .LBB0_95
	s_mul_i32 s3, s45, 0x380000
	s_mul_hi_i32 s2, s45, 0x380000
	s_add_u32 s3, s4, s3
	s_addc_u32 s2, s5, s2
	s_add_u32 s8, s3, 0xb00000
	s_addc_u32 s9, s2, 0
	v_writelane_b32 v254, s8, 54
	s_mov_b32 s27, 0
	v_writelane_b32 v254, s9, 55
	s_nop 1
	v_readlane_b32 s8, v254, 23
	s_cmp_lt_u32 s8, 0x50
	s_cbranch_scc1 .Lrb_A
	s_cmp_lt_u32 s8, 0x80
	s_cbranch_scc1 .Lrb_B
	s_cmp_lt_u32 s8, 0x90
	s_cbranch_scc1 .Lrb_V4a
	s_cmp_lt_u32 s8, 0xd0
	s_cbranch_scc1 .Lrb_N
	s_lshl_b32 s2, s8, 2
	s_add_i32 s2, s2, 0xfffffdc0
	s_branch .Lrb_V4
.Lrb_V4a:
	s_lshl_b32 s2, s8, 2
	s_add_i32 s2, s2, 0xfffffec0
.Lrb_V4:
	s_mov_b32 s73, 0
	s_mov_b32 s14, 0
	s_mov_b32 s3, 4
	s_branch .Lrb_noe

.Lrb_B:
	s_mul_i32 s73, s8, 3
	s_add_i32 s73, s73, 0xffffffa0
	s_mov_b32 s14, 3
	s_mov_b32 s2, 0
	s_mov_b32 s3, 0

.Lrb_N:
	s_add_i32 s73, s8, 0xffffffc0
	s_mov_b32 s14, 1
	s_lshl_b32 s2, s8, 1
	s_add_i32 s2, s2, 0xffffff20
	s_mov_b32 s3, 2
	v_writelane_b32 v254, s2, 63
	v_writelane_b32 v254, s3, 62
	s_mov_b32 s2, 1
	v_writelane_b32 v254, s2, 35
	s_add_i32 s2, s8, 0xffffff70
	v_writelane_b32 v254, s2, 43
	s_branch .LBB0_1658
